# LayerNorm prompt rows: the four bf16 source rows staged in the wave's own LDS by 16 LDS-DMA loads issued together, compiled row code reads its pieces from LDS (replaces the touch-prefetch)
# baseline (speedup 1.0000x reference)
.LBB0_155:
	v_lshl_add_u64 v[2:3], s[66:67], 0, v[36:37]
	s_mov_b64 s[0:1], 0x2600000
	v_lshl_add_u64 v[10:11], v[2:3], 0, s[0:1]
	v_add_co_u32_e32 v2, vcc, 0x2600000, v2
	s_mov_b64 s[0:1], 0xe00
	s_nop 0
	v_addc_co_u32_e32 v3, vcc, 0, v3, vcc
	v_lshl_add_u64 v[220:221], s[66:67], 0, v[14:15]
	v_add_co_u32_e32 v220, vcc, 0x2600000, v220
	s_nop 0
	v_addc_co_u32_e32 v221, vcc, 0, v221, vcc
	v_lshrrev_b32_e32 v222, 6, v219
	v_lshlrev_b32_e32 v222, 14, v222
	v_lshl_add_u32 v222, v138, 3, v222
	s_nop 0
	v_readfirstlane_b32 vcc_lo, v222
	s_nop 3
	s_mov_b32 m0, vcc_lo
	s_nop 0
	global_load_lds_dwordx4 v[220:221], off
	global_load_lds_dwordx4 v[220:221], off offset:1024
	global_load_lds_dwordx4 v[220:221], off offset:2048
	global_load_lds_dwordx4 v[220:221], off offset:3072
	s_add_i32 m0, m0, 0x1000
	v_lshl_add_u64 v[220:221], v[220:221], 0, s[70:71]
	s_nop 0
	global_load_lds_dwordx4 v[220:221], off
	global_load_lds_dwordx4 v[220:221], off offset:1024
	global_load_lds_dwordx4 v[220:221], off offset:2048
	global_load_lds_dwordx4 v[220:221], off offset:3072
	s_add_i32 m0, m0, 0x1000
	v_lshl_add_u64 v[220:221], v[220:221], 0, s[70:71]
	s_nop 0
	global_load_lds_dwordx4 v[220:221], off
	global_load_lds_dwordx4 v[220:221], off offset:1024
	global_load_lds_dwordx4 v[220:221], off offset:2048
	global_load_lds_dwordx4 v[220:221], off offset:3072
	s_add_i32 m0, m0, 0x1000
	v_lshl_add_u64 v[220:221], v[220:221], 0, s[70:71]
	s_nop 0
	global_load_lds_dwordx4 v[220:221], off
	global_load_lds_dwordx4 v[220:221], off offset:1024
	global_load_lds_dwordx4 v[220:221], off offset:2048
	global_load_lds_dwordx4 v[220:221], off offset:3072
	s_waitcnt vmcnt(0)
	ds_read_b64 v[4:5], v222
	ds_read_b64 v[6:7], v222 offset:512
	s_nop 0
	ds_read_b64 v[2:3], v222 offset:1024
	ds_read_b64 v[8:9], v222 offset:1536
	s_andn2_b64 vcc, exec, s[22:23]
	s_waitcnt lgkmcnt(0)
	v_lshlrev_b32_e32 v116, 16, v4
	v_lshlrev_b32_e32 v117, 16, v6
	v_and_b32_e32 v179, 0xffff0000, v6
	v_lshlrev_b32_e32 v112, 16, v8
	v_and_b32_e32 v113, 0xffff0000, v8
	v_lshlrev_b32_e32 v110, 16, v9
	v_and_b32_e32 v111, 0xffff0000, v9
	ds_read_b64 v[8:9], v222 offset:2048
	v_and_b32_e32 v178, 0xffff0000, v4
	v_lshlrev_b32_e32 v162, 16, v5
	v_lshlrev_b32_e32 v163, 16, v7
	v_and_b32_e32 v181, 0xffff0000, v7
	v_and_b32_e32 v180, 0xffff0000, v5
	v_pk_add_f32 v[4:5], v[116:117], v[178:179]
	v_pk_add_f32 v[6:7], v[162:163], v[180:181]
	v_lshlrev_b32_e32 v157, 16, v3
	v_lshlrev_b32_e32 v156, 16, v2
	v_and_b32_e32 v147, 0xffff0000, v3
	v_and_b32_e32 v146, 0xffff0000, v2
	v_pk_add_f32 v[4:5], v[4:5], v[6:7]
	v_pk_add_f32 v[2:3], v[156:157], v[146:147]
	v_add_f32_e32 v0, 0, v4
	v_pk_add_f32 v[2:3], v[2:3], v[2:3] op_sel:[0,1] op_sel_hi:[1,0]
	v_add_f32_e32 v88, v0, v5
	v_add_f32_e32 v86, v112, v113
	v_add_f32_e32 v84, v110, v111
	s_waitcnt lgkmcnt(0)
	v_lshlrev_b32_e32 v89, 16, v8
	v_and_b32_e32 v83, 0xffff0000, v8
	v_lshlrev_b32_e32 v87, 16, v9
	v_and_b32_e32 v85, 0xffff0000, v9
	ds_read_b64 v[8:9], v222 offset:2560
	ds_read_b64 v[12:13], v222 offset:3072
	v_mov_b32_e32 v3, v83
	v_pk_add_f32 v[2:3], v[88:89], v[2:3]
	v_pk_add_f32 v[4:5], v[86:87], v[84:85]
	s_waitcnt lgkmcnt(1)
	v_lshlrev_b32_e32 v141, 16, v9
	s_waitcnt lgkmcnt(0)
	v_lshlrev_b32_e32 v58, 16, v12
	v_and_b32_e32 v59, 0xffff0000, v12
	v_lshlrev_b32_e32 v60, 16, v13
	v_and_b32_e32 v61, 0xffff0000, v13
	v_lshl_add_u64 v[12:13], v[10:11], 0, s[0:1]
	ds_read_b64 v[10:11], v222 offset:3584
	v_lshl_add_u64 v[38:39], v[12:13], 0, s[82:83]
	v_lshl_add_u64 v[50:51], v[38:39], 0, s[0:1]
	v_lshl_add_u64 v[50:51], v[50:51], 0, s[82:83]
	v_lshl_add_u64 v[68:69], v[50:51], 0, s[0:1]
	v_lshl_add_u64 v[70:71], v[68:69], 0, s[82:83]
	v_lshlrev_b32_e32 v140, 16, v8
	v_and_b32_e32 v143, 0xffff0000, v9
	v_and_b32_e32 v142, 0xffff0000, v8
	v_pk_add_f32 v[2:3], v[2:3], v[4:5]
	v_pk_add_f32 v[4:5], v[140:141], v[142:143]
	v_pk_add_f32 v[2:3], v[2:3], v[2:3] op_sel:[0,1] op_sel_hi:[1,0]
	v_pk_add_f32 v[4:5], v[4:5], v[4:5] op_sel:[0,1] op_sel_hi:[1,0]
	v_add_f32_e32 v46, v58, v59
	v_add_f32_e32 v44, v60, v61
	s_waitcnt lgkmcnt(0)
	v_lshlrev_b32_e32 v42, 16, v10
	v_and_b32_e32 v43, 0xffff0000, v10
	v_lshlrev_b32_e32 v47, 16, v11
	v_and_b32_e32 v45, 0xffff0000, v11
	ds_read_b64 v[12:13], v222 offset:4096
	ds_read_b64 v[124:125], v222 offset:4608
	ds_read_b64 v[10:11], v222 offset:5120
	ds_read_b64 v[40:41], v222 offset:5632
	v_mov_b32_e32 v3, v42
	v_mov_b32_e32 v5, v43
	v_pk_add_f32 v[2:3], v[2:3], v[4:5]
	v_pk_add_f32 v[4:5], v[46:47], v[44:45]
	s_waitcnt lgkmcnt(3)
	v_lshlrev_b32_e32 v200, 16, v12
	v_pk_add_f32 v[2:3], v[2:3], v[4:5]
	s_waitcnt lgkmcnt(2)
	v_lshlrev_b32_e32 v201, 16, v124
	s_waitcnt lgkmcnt(0)
	v_lshlrev_b32_e32 v118, 16, v40
	v_and_b32_e32 v119, 0xffff0000, v40
	v_lshlrev_b32_e32 v114, 16, v41
	v_and_b32_e32 v115, 0xffff0000, v41
	ds_read_b64 v[40:41], v222 offset:6144
	v_add_f32_e32 v0, v2, v3
	v_and_b32_e32 v189, 0xffff0000, v124
	v_and_b32_e32 v188, 0xffff0000, v12
	v_add_f32_dpp v0, v0, v0 quad_perm:[1,0,3,2] row_mask:0xf bank_mask:0xf bound_ctrl:1
	v_lshlrev_b32_e32 v151, 16, v125
	v_lshlrev_b32_e32 v150, 16, v13
	v_add_f32_dpp v0, v0, v0 quad_perm:[2,3,0,1] row_mask:0xf bank_mask:0xf bound_ctrl:1
	v_and_b32_e32 v177, 0xffff0000, v125
	v_and_b32_e32 v176, 0xffff0000, v13
	v_add_f32_dpp v0, v0, v0 row_half_mirror row_mask:0xf bank_mask:0xf bound_ctrl:1
	v_pk_add_f32 v[4:5], v[150:151], v[176:177]
	v_lshlrev_b32_e32 v155, 16, v11
	v_add_f32_dpp v0, v0, v0 row_ror:8 row_mask:0xf bank_mask:0xf bound_ctrl:1
	v_lshlrev_b32_e32 v154, 16, v10
	v_readlane_b32 s2, v0, 16
	v_readlane_b32 s3, v0, 48
	v_readlane_b32 s0, v0, 0
	v_readlane_b32 s1, v0, 32
	v_mov_b32_e32 v2, s2
	v_mov_b32_e32 v3, s3
	v_pk_add_f32 v[2:3], s[0:1], v[2:3]
	v_and_b32_e32 v153, 0xffff0000, v11
	v_add_f32_e32 v0, v2, v3
	v_pk_add_f32 v[2:3], v[200:201], v[188:189]
	v_and_b32_e32 v152, 0xffff0000, v10
	v_pk_add_f32 v[2:3], v[2:3], v[4:5]
	v_add_f32_e32 v80, v118, v119
	v_add_f32_e32 v2, 0, v2
	v_add_f32_e32 v104, v2, v3
	v_pk_add_f32 v[2:3], v[154:155], v[152:153]
	v_add_f32_e32 v78, v114, v115
	v_pk_add_f32 v[2:3], v[2:3], v[2:3] op_sel:[0,1] op_sel_hi:[1,0]
	v_fmac_f32_e32 v146, 0xba000000, v0
	v_fmac_f32_e32 v156, 0xba000000, v0
	v_fmac_f32_e32 v147, 0xba000000, v0
	v_fmac_f32_e32 v157, 0xba000000, v0
	v_mov_b32_e32 v6, v156
	v_mov_b32_e32 v7, v146
	v_pk_mul_f32 v[6:7], v[6:7], v[6:7]
	v_mov_b32_e32 v8, v157
	v_mov_b32_e32 v9, v147
	v_fmac_f32_e32 v113, 0xba000000, v0
	v_fmac_f32_e32 v112, 0xba000000, v0
	v_pk_fma_f32 v[6:7], v[8:9], v[8:9], v[6:7]
	v_fmac_f32_e32 v111, 0xba000000, v0
	v_fmac_f32_e32 v110, 0xba000000, v0
	v_pk_mul_f32 v[8:9], v[112:113], v[112:113]
	v_fmac_f32_e32 v178, 0xba000000, v0
	v_fmac_f32_e32 v116, 0xba000000, v0
	v_fmac_f32_e32 v117, 0xba000000, v0
	v_pk_fma_f32 v[8:9], v[110:111], v[110:111], v[8:9]
	v_fmac_f32_e32 v180, 0xba000000, v0
	v_fmac_f32_e32 v162, 0xba000000, v0
	v_mov_b32_e32 v10, v116
	v_mov_b32_e32 v11, v178
	v_fmac_f32_e32 v163, 0xba000000, v0
	v_fmac_f32_e32 v179, 0xba000000, v0
	v_mov_b32_e32 v178, v117
	v_fmac_f32_e32 v89, 0xba000000, v0
	v_fmac_f32_e32 v142, 0xba000000, v0
	v_fmac_f32_e32 v140, 0xba000000, v0
	v_mov_b32_e32 v12, v162
	v_mov_b32_e32 v13, v180
	v_fmac_f32_e32 v181, 0xba000000, v0
	v_mov_b32_e32 v180, v163
	v_fmac_f32_e32 v87, 0xba000000, v0
	v_fmac_f32_e32 v83, 0xba000000, v0
	v_mov_b32_e32 v82, v89
	v_fmac_f32_e32 v143, 0xba000000, v0
	v_fmac_f32_e32 v141, 0xba000000, v0
	v_fmac_f32_e32 v85, 0xba000000, v0
	v_mov_b32_e32 v84, v87
	v_fmac_f32_e32 v61, 0xba000000, v0
	v_fmac_f32_e32 v60, 0xba000000, v0
	v_fmac_f32_e32 v59, 0xba000000, v0
	v_fmac_f32_e32 v58, 0xba000000, v0
	v_fmac_f32_e32 v45, 0xba000000, v0
	v_fmac_f32_e32 v47, 0xba000000, v0
	v_fmac_f32_e32 v43, 0xba000000, v0
	s_waitcnt lgkmcnt(0)
	v_lshlrev_b32_e32 v105, 16, v40
	v_and_b32_e32 v91, 0xffff0000, v40
	v_lshlrev_b32_e32 v81, 16, v41
	v_and_b32_e32 v79, 0xffff0000, v41
	ds_read_b64 v[130:131], v222 offset:6656
	ds_read_b64 v[40:41], v222 offset:7168
	v_mov_b32_e32 v3, v91
	ds_read_b64 v[38:39], v222 offset:7680
	s_nop 0
	ds_read_b64 v[134:135], v222 offset:8192
	ds_read_b64 v[136:137], v222 offset:8704
	ds_read_b64 v[132:133], v222 offset:9216
	ds_read_b64 v[52:53], v222 offset:9728
	v_pk_add_f32 v[2:3], v[104:105], v[2:3]
	v_pk_add_f32 v[4:5], v[80:81], v[78:79]
	v_fmac_f32_e32 v42, 0xba000000, v0
	v_pk_add_f32 v[2:3], v[2:3], v[4:5]
	v_mov_b32_e32 v44, v47
	v_pk_add_f32 v[2:3], v[2:3], v[2:3] op_sel:[0,1] op_sel_hi:[1,0]
	s_waitcnt lgkmcnt(6)
	v_lshlrev_b32_e32 v127, 16, v131
	v_lshlrev_b32_e32 v126, 16, v130
	v_and_b32_e32 v125, 0xffff0000, v131
	v_and_b32_e32 v124, 0xffff0000, v130
	s_waitcnt lgkmcnt(0)
	v_lshlrev_b32_e32 v120, 16, v52
	v_and_b32_e32 v121, 0xffff0000, v52
	v_lshlrev_b32_e32 v122, 16, v53
	v_and_b32_e32 v123, 0xffff0000, v53
	ds_read_b64 v[52:53], v222 offset:10240
	v_pk_add_f32 v[4:5], v[126:127], v[124:125]
	v_lshlrev_b32_e32 v62, 16, v40
	v_and_b32_e32 v63, 0xffff0000, v40
	v_lshlrev_b32_e32 v56, 16, v41
	v_and_b32_e32 v57, 0xffff0000, v41
	v_lshlrev_b32_e32 v48, 16, v38
	v_and_b32_e32 v49, 0xffff0000, v38
	v_pk_add_f32 v[4:5], v[4:5], v[4:5] op_sel:[0,1] op_sel_hi:[1,0]
	v_lshlrev_b32_e32 v41, 16, v39
	v_and_b32_e32 v39, 0xffff0000, v39
	v_add_f32_e32 v40, v62, v63
	v_add_f32_e32 v38, v56, v57
	v_mov_b32_e32 v3, v48
	v_mov_b32_e32 v5, v49
	v_pk_add_f32 v[2:3], v[2:3], v[4:5]
	v_pk_add_f32 v[4:5], v[40:41], v[38:39]
	v_lshlrev_b32_e32 v195, 16, v136
	v_pk_add_f32 v[2:3], v[2:3], v[4:5]
	v_lshlrev_b32_e32 v194, 16, v134
	v_add_f32_e32 v2, v2, v3
	v_and_b32_e32 v183, 0xffff0000, v136
	v_and_b32_e32 v182, 0xffff0000, v134
	v_add_f32_dpp v2, v2, v2 quad_perm:[1,0,3,2] row_mask:0xf bank_mask:0xf bound_ctrl:1
	v_lshlrev_b32_e32 v187, 16, v137
	v_lshlrev_b32_e32 v186, 16, v135
	v_add_f32_dpp v2, v2, v2 quad_perm:[2,3,0,1] row_mask:0xf bank_mask:0xf bound_ctrl:1
	v_and_b32_e32 v185, 0xffff0000, v137
	v_and_b32_e32 v184, 0xffff0000, v135
	v_add_f32_dpp v2, v2, v2 row_half_mirror row_mask:0xf bank_mask:0xf bound_ctrl:1
	v_pk_add_f32 v[4:5], v[186:187], v[184:185]
	v_lshlrev_b32_e32 v169, 16, v133
	v_add_f32_dpp v2, v2, v2 row_ror:8 row_mask:0xf bank_mask:0xf bound_ctrl:1
	v_lshlrev_b32_e32 v168, 16, v132
	v_readlane_b32 s2, v2, 16
	v_readlane_b32 s3, v2, 48
	v_readlane_b32 s0, v2, 0
	v_readlane_b32 s1, v2, 32
	v_mov_b32_e32 v2, s2
	v_mov_b32_e32 v3, s3
	v_pk_add_f32 v[2:3], s[0:1], v[2:3]
	v_and_b32_e32 v167, 0xffff0000, v133
	v_add_f32_e32 v38, v2, v3
	v_pk_add_f32 v[2:3], v[194:195], v[182:183]
	v_and_b32_e32 v166, 0xffff0000, v132
	v_pk_add_f32 v[2:3], v[2:3], v[4:5]
	v_add_f32_e32 v96, v120, v121
	v_add_f32_e32 v2, 0, v2
	v_add_f32_e32 v98, v2, v3
	v_pk_add_f32 v[2:3], v[168:169], v[166:167]
	v_add_f32_e32 v94, v122, v123
	v_pk_add_f32 v[2:3], v[2:3], v[2:3] op_sel:[0,1] op_sel_hi:[1,0]
	v_fmac_f32_e32 v188, 0xba000000, v38
	v_fmac_f32_e32 v200, 0xba000000, v38
	v_fmac_f32_e32 v189, 0xba000000, v38
	v_fmac_f32_e32 v201, 0xba000000, v38
	v_fmac_f32_e32 v176, 0xba000000, v38
	v_fmac_f32_e32 v150, 0xba000000, v38
	v_fmac_f32_e32 v151, 0xba000000, v38
	v_fmac_f32_e32 v152, 0xba000000, v38
	v_fmac_f32_e32 v154, 0xba000000, v38
	v_fmac_f32_e32 v177, 0xba000000, v38
	v_fmac_f32_e32 v153, 0xba000000, v38
	v_fmac_f32_e32 v155, 0xba000000, v38
	v_fmac_f32_e32 v119, 0xba000000, v38
	v_fmac_f32_e32 v118, 0xba000000, v38
	v_fmac_f32_e32 v105, 0xba000000, v38
	v_fmac_f32_e32 v115, 0xba000000, v38
	v_fmac_f32_e32 v114, 0xba000000, v38
	v_fmac_f32_e32 v81, 0xba000000, v38
	v_fmac_f32_e32 v91, 0xba000000, v38
	v_mov_b32_e32 v90, v105
	v_fmac_f32_e32 v124, 0xba000000, v38
	v_fmac_f32_e32 v126, 0xba000000, v38
	v_fmac_f32_e32 v79, 0xba000000, v38
	v_mov_b32_e32 v78, v81
	v_fmac_f32_e32 v125, 0xba000000, v38
	v_fmac_f32_e32 v127, 0xba000000, v38
	v_fmac_f32_e32 v63, 0xba000000, v38
	v_fmac_f32_e32 v62, 0xba000000, v38
	s_waitcnt lgkmcnt(0)
	v_lshlrev_b32_e32 v99, 16, v52
	v_and_b32_e32 v93, 0xffff0000, v52
	v_lshlrev_b32_e32 v97, 16, v53
	v_and_b32_e32 v95, 0xffff0000, v53
	ds_read_b64 v[148:149], v222 offset:10752
	ds_read_b64 v[52:53], v222 offset:11264
	v_mov_b32_e32 v3, v93
	v_pk_add_f32 v[2:3], v[98:99], v[2:3]
	v_pk_add_f32 v[4:5], v[96:97], v[94:95]
	v_fmac_f32_e32 v57, 0xba000000, v38
	v_pk_add_f32 v[2:3], v[2:3], v[4:5]
	v_fmac_f32_e32 v56, 0xba000000, v38
	v_pk_add_f32 v[2:3], v[2:3], v[2:3] op_sel:[0,1] op_sel_hi:[1,0]
	v_fmac_f32_e32 v41, 0xba000000, v38
	v_fmac_f32_e32 v49, 0xba000000, v38
	v_fmac_f32_e32 v48, 0xba000000, v38
	v_fmac_f32_e32 v39, 0xba000000, v38
	v_mov_b32_e32 v38, v41
	s_waitcnt lgkmcnt(1)
	v_lshlrev_b32_e32 v137, 16, v149
	s_waitcnt lgkmcnt(0)
	v_lshlrev_b32_e32 v64, 16, v52
	v_and_b32_e32 v65, 0xffff0000, v52
	v_lshlrev_b32_e32 v66, 16, v53
	v_and_b32_e32 v67, 0xffff0000, v53
	ds_read_b64 v[52:53], v222 offset:11776
	ds_read_b64 v[160:161], v222 offset:12288
	ds_read_b64 v[164:165], v222 offset:12800
	ds_read_b64 v[158:159], v222 offset:13312
	ds_read_b64 v[68:69], v222 offset:13824
	v_lshlrev_b32_e32 v136, 16, v148
	v_and_b32_e32 v135, 0xffff0000, v149
	v_and_b32_e32 v134, 0xffff0000, v148
	v_pk_add_f32 v[4:5], v[136:137], v[134:135]
	v_add_f32_e32 v54, v64, v65
	v_pk_add_f32 v[4:5], v[4:5], v[4:5] op_sel:[0,1] op_sel_hi:[1,0]
	v_mov_b32_e32 v148, v8
	v_mov_b32_e32 v149, v6
	v_mov_b32_e32 v6, v9
	v_pk_add_f32 v[6:7], v[148:149], v[6:7]
	v_mov_b32_e32 v148, v140
	v_mov_b32_e32 v149, v142
	v_pk_mul_f32 v[8:9], v[82:83], v[82:83]
	v_pk_mul_f32 v[148:149], v[148:149], v[148:149]
	v_pk_fma_f32 v[8:9], v[84:85], v[84:85], v[8:9]
	s_waitcnt lgkmcnt(3)
	v_lshlrev_b32_e32 v198, 16, v160
	s_waitcnt lgkmcnt(2)
	v_lshlrev_b32_e32 v199, 16, v164
	v_lshlrev_b32_e32 v50, 16, v52
	s_waitcnt lgkmcnt(0)
	v_lshlrev_b32_e32 v144, 16, v68
	v_and_b32_e32 v145, 0xffff0000, v68
	v_lshlrev_b32_e32 v128, 16, v69
	v_and_b32_e32 v129, 0xffff0000, v69
	ds_read_b64 v[68:69], v222 offset:14336
	v_and_b32_e32 v51, 0xffff0000, v52
	v_lshlrev_b32_e32 v55, 16, v53
	v_and_b32_e32 v53, 0xffff0000, v53
	v_add_f32_e32 v52, v66, v67
	v_mov_b32_e32 v3, v50
	v_mov_b32_e32 v5, v51
	v_pk_add_f32 v[2:3], v[2:3], v[4:5]
	v_pk_add_f32 v[4:5], v[54:55], v[52:53]
	v_and_b32_e32 v197, 0xffff0000, v164
	v_pk_add_f32 v[2:3], v[2:3], v[4:5]
	v_and_b32_e32 v196, 0xffff0000, v160
	v_add_f32_e32 v2, v2, v3
	v_lshlrev_b32_e32 v193, 16, v165
	v_lshlrev_b32_e32 v192, 16, v161
	v_add_f32_dpp v2, v2, v2 quad_perm:[1,0,3,2] row_mask:0xf bank_mask:0xf bound_ctrl:1
	v_and_b32_e32 v191, 0xffff0000, v165
	v_and_b32_e32 v190, 0xffff0000, v161
	v_add_f32_dpp v2, v2, v2 quad_perm:[2,3,0,1] row_mask:0xf bank_mask:0xf bound_ctrl:1
	v_pk_add_f32 v[4:5], v[192:193], v[190:191]
	v_lshlrev_b32_e32 v173, 16, v159
	v_add_f32_dpp v2, v2, v2 row_half_mirror row_mask:0xf bank_mask:0xf bound_ctrl:1
	v_lshlrev_b32_e32 v172, 16, v158
	v_and_b32_e32 v171, 0xffff0000, v159
	v_add_f32_dpp v2, v2, v2 row_ror:8 row_mask:0xf bank_mask:0xf bound_ctrl:1
	v_and_b32_e32 v170, 0xffff0000, v158
	v_readlane_b32 s2, v2, 16
	v_readlane_b32 s3, v2, 48
	v_readlane_b32 s0, v2, 0
	v_readlane_b32 s1, v2, 32
	v_mov_b32_e32 v2, s2
	v_mov_b32_e32 v3, s3
	v_pk_add_f32 v[2:3], s[0:1], v[2:3]
	v_add_f32_e32 v102, v144, v145
	v_add_f32_e32 v40, v2, v3
	v_pk_add_f32 v[2:3], v[198:199], v[196:197]
	v_add_f32_e32 v100, v128, v129
	v_pk_add_f32 v[2:3], v[2:3], v[4:5]
	v_mov_b32_e32 v158, v141
	v_add_f32_e32 v2, 0, v2
	v_add_f32_e32 v108, v2, v3
	v_pk_add_f32 v[2:3], v[172:173], v[170:171]
	v_mov_b32_e32 v159, v143
	v_pk_add_f32 v[2:3], v[2:3], v[2:3] op_sel:[0,1] op_sel_hi:[1,0]
	v_pk_fma_f32 v[148:149], v[158:159], v[158:159], v[148:149]
	v_mov_b32_e32 v159, v8
	v_mov_b32_e32 v158, v148
	v_mov_b32_e32 v8, v149
	v_pk_add_f32 v[8:9], v[158:159], v[8:9]
	v_pk_mul_f32 v[148:149], v[58:59], v[58:59]
	v_pk_mul_f32 v[158:159], v[42:43], v[42:43]
	v_pk_fma_f32 v[148:149], v[60:61], v[60:61], v[148:149]
	v_pk_fma_f32 v[158:159], v[44:45], v[44:45], v[158:159]
	v_mov_b32_e32 v161, v148
	v_mov_b32_e32 v160, v158
	v_mov_b32_e32 v148, v159
	v_pk_add_f32 v[148:149], v[160:161], v[148:149]
	v_pk_mul_f32 v[158:159], v[90:91], v[90:91]
	v_mov_b32_e32 v160, v126
	v_mov_b32_e32 v161, v124
	v_pk_fma_f32 v[158:159], v[78:79], v[78:79], v[158:159]
	v_pk_mul_f32 v[160:161], v[160:161], v[160:161]
	v_mov_b32_e32 v164, v127
	v_mov_b32_e32 v165, v125
	v_pk_fma_f32 v[160:161], v[164:165], v[164:165], v[160:161]
	v_pk_mul_f32 v[164:165], v[62:63], v[62:63]
	v_fmac_f32_e32 v182, 0xba000000, v40
	v_pk_fma_f32 v[164:165], v[56:57], v[56:57], v[164:165]
	v_fmac_f32_e32 v194, 0xba000000, v40
	v_fmac_f32_e32 v184, 0xba000000, v40
	v_fmac_f32_e32 v186, 0xba000000, v40
	v_fmac_f32_e32 v183, 0xba000000, v40
	v_fmac_f32_e32 v195, 0xba000000, v40
	v_fmac_f32_e32 v185, 0xba000000, v40
	v_fmac_f32_e32 v187, 0xba000000, v40
	v_fmac_f32_e32 v166, 0xba000000, v40
	v_fmac_f32_e32 v168, 0xba000000, v40
	v_fmac_f32_e32 v167, 0xba000000, v40
	v_fmac_f32_e32 v169, 0xba000000, v40
	v_fmac_f32_e32 v121, 0xba000000, v40
	s_waitcnt lgkmcnt(0)
	v_lshlrev_b32_e32 v109, 16, v68
	v_and_b32_e32 v107, 0xffff0000, v68
	v_lshlrev_b32_e32 v103, 16, v69
	v_and_b32_e32 v101, 0xffff0000, v69
	ds_read_b64 v[174:175], v222 offset:14848
	ds_read_b64 v[68:69], v222 offset:15360
	v_mov_b32_e32 v3, v107
	ds_read_b64 v[70:71], v222 offset:15872
	v_pk_add_f32 v[2:3], v[108:109], v[2:3]
	v_pk_add_f32 v[4:5], v[102:103], v[100:101]
	v_fmac_f32_e32 v120, 0xba000000, v40
	v_pk_add_f32 v[2:3], v[2:3], v[4:5]
	v_fmac_f32_e32 v99, 0xba000000, v40
	v_pk_add_f32 v[2:3], v[2:3], v[2:3] op_sel:[0,1] op_sel_hi:[1,0]
	v_fmac_f32_e32 v123, 0xba000000, v40
	v_fmac_f32_e32 v122, 0xba000000, v40
	v_fmac_f32_e32 v97, 0xba000000, v40
	v_fmac_f32_e32 v93, 0xba000000, v40
	v_mov_b32_e32 v92, v99
	v_fmac_f32_e32 v134, 0xba000000, v40
	v_fmac_f32_e32 v136, 0xba000000, v40
	v_fmac_f32_e32 v95, 0xba000000, v40
	v_mov_b32_e32 v94, v97
	v_fmac_f32_e32 v135, 0xba000000, v40
	v_fmac_f32_e32 v137, 0xba000000, v40
	v_fmac_f32_e32 v65, 0xba000000, v40
	v_fmac_f32_e32 v64, 0xba000000, v40
	v_fmac_f32_e32 v67, 0xba000000, v40
	v_fmac_f32_e32 v66, 0xba000000, v40
	v_fmac_f32_e32 v55, 0xba000000, v40
	v_fmac_f32_e32 v51, 0xba000000, v40
	v_fmac_f32_e32 v50, 0xba000000, v40
	v_fmac_f32_e32 v53, 0xba000000, v40
	v_mov_b32_e32 v52, v55
	s_waitcnt lgkmcnt(2)
	v_lshlrev_b32_e32 v133, 16, v175
	v_lshlrev_b32_e32 v132, 16, v174
	v_and_b32_e32 v131, 0xffff0000, v175
	v_and_b32_e32 v130, 0xffff0000, v174
	v_pk_add_f32 v[4:5], v[132:133], v[130:131]
	s_waitcnt lgkmcnt(1)
	v_lshlrev_b32_e32 v74, 16, v68
	v_and_b32_e32 v75, 0xffff0000, v68
	v_lshlrev_b32_e32 v68, 16, v69
	v_and_b32_e32 v69, 0xffff0000, v69
	s_waitcnt lgkmcnt(0)
	v_lshlrev_b32_e32 v76, 16, v70
	v_and_b32_e32 v77, 0xffff0000, v70
	v_pk_add_f32 v[4:5], v[4:5], v[4:5] op_sel:[0,1] op_sel_hi:[1,0]
	v_lshlrev_b32_e32 v73, 16, v71
	v_and_b32_e32 v71, 0xffff0000, v71
	v_add_f32_e32 v72, v74, v75
	v_add_f32_e32 v70, v68, v69
	v_mov_b32_e32 v3, v76
	v_mov_b32_e32 v5, v77
	v_pk_add_f32 v[2:3], v[2:3], v[4:5]
	v_pk_add_f32 v[4:5], v[72:73], v[70:71]
	v_pk_mul_f32 v[174:175], v[48:49], v[48:49]
	v_pk_add_f32 v[2:3], v[2:3], v[4:5]
	v_pk_mul_f32 v[4:5], v[178:179], v[178:179]
	v_add_f32_e32 v2, v2, v3
	v_pk_fma_f32 v[4:5], v[180:181], v[180:181], v[4:5]
	v_pk_fma_f32 v[174:175], v[38:39], v[38:39], v[174:175]
	v_add_f32_dpp v2, v2, v2 quad_perm:[1,0,3,2] row_mask:0xf bank_mask:0xf bound_ctrl:1
	v_add_f32_e32 v0, v4, v5
	v_mov_b32_e32 v4, v201
	v_add_f32_dpp v2, v2, v2 quad_perm:[2,3,0,1] row_mask:0xf bank_mask:0xf bound_ctrl:1
	v_mov_b32_e32 v5, v189
	v_pk_mul_f32 v[4:5], v[4:5], v[4:5]
	v_add_f32_dpp v2, v2, v2 row_half_mirror row_mask:0xf bank_mask:0xf bound_ctrl:1
	s_nop 1
	v_add_f32_dpp v2, v2, v2 row_ror:8 row_mask:0xf bank_mask:0xf bound_ctrl:1
	s_nop 0
	v_readlane_b32 s2, v2, 16
	v_readlane_b32 s3, v2, 48
	v_readlane_b32 s0, v2, 0
	v_readlane_b32 s1, v2, 32
	v_mov_b32_e32 v2, s2
	v_mov_b32_e32 v3, s3
	v_pk_add_f32 v[2:3], s[0:1], v[2:3]
	s_nop 0
	v_add_f32_e32 v46, v2, v3
	v_pk_mul_f32 v[2:3], v[10:11], v[10:11]
	v_fmac_f32_e32 v196, 0xba000000, v46
	v_pk_fma_f32 v[2:3], v[12:13], v[12:13], v[2:3]
	v_fmac_f32_e32 v198, 0xba000000, v46
	v_add_f32_e32 v2, v2, v3
	v_add_f32_e32 v0, v2, v0
	v_add_f32_e32 v0, v7, v0
	v_add_f32_e32 v0, v6, v0
	v_add_f32_e32 v0, v9, v0
	v_add_f32_e32 v0, v8, v0
	v_add_f32_e32 v0, v149, v0
	v_add_f32_e32 v0, v148, v0
	v_mov_b32_e32 v148, v150
	v_mov_b32_e32 v149, v176
	v_add_f32_dpp v0, v0, v0 quad_perm:[1,0,3,2] row_mask:0xf bank_mask:0xf bound_ctrl:1
	v_mov_b32_e32 v176, v151
	v_mov_b32_e32 v6, v154
	v_add_f32_dpp v0, v0, v0 quad_perm:[2,3,0,1] row_mask:0xf bank_mask:0xf bound_ctrl:1
	v_mov_b32_e32 v7, v152
	v_pk_fma_f32 v[4:5], v[176:177], v[176:177], v[4:5]
	v_add_f32_dpp v0, v0, v0 row_half_mirror row_mask:0xf bank_mask:0xf bound_ctrl:1
	v_pk_mul_f32 v[6:7], v[6:7], v[6:7]
	v_mov_b32_e32 v8, v155
	v_add_f32_dpp v0, v0, v0 row_ror:8 row_mask:0xf bank_mask:0xf bound_ctrl:1
	v_mov_b32_e32 v9, v153
	v_readlane_b32 s2, v0, 16
	v_readlane_b32 s3, v0, 48
	v_readlane_b32 s0, v0, 0
	v_readlane_b32 s1, v0, 32
	v_mov_b32_e32 v2, s2
	v_mov_b32_e32 v3, s3
	v_pk_add_f32 v[2:3], s[0:1], v[2:3]
	v_pk_fma_f32 v[6:7], v[8:9], v[8:9], v[6:7]
	v_add_f32_e32 v0, v2, v3
	v_mov_b32_e32 v2, v200
	v_mov_b32_e32 v3, v188
	v_pk_mul_f32 v[2:3], v[2:3], v[2:3]
	v_fmamk_f32 v0, v0, 0x3a000000, v203
	v_pk_fma_f32 v[2:3], v[148:149], v[148:149], v[2:3]
	v_rsq_f32_e32 v116, v0
	v_pk_mul_f32 v[8:9], v[118:119], v[118:119]
	v_add_f32_e32 v0, v4, v5
	v_add_f32_e32 v2, v2, v3
	v_pk_fma_f32 v[8:9], v[114:115], v[114:115], v[8:9]
	v_add_f32_e32 v0, v2, v0
	v_add_f32_e32 v2, v6, v7
	v_add_f32_e32 v0, v2, v0
	v_add_f32_e32 v2, v8, v9
	v_add_f32_e32 v0, v2, v0
	v_add_f32_e32 v2, v158, v159
	v_add_f32_e32 v0, v2, v0
	v_add_f32_e32 v2, v160, v161
	v_add_f32_e32 v0, v2, v0
	v_add_f32_e32 v2, v164, v165
	v_add_f32_e32 v0, v2, v0
	v_add_f32_e32 v2, v174, v175
	v_add_f32_e32 v0, v2, v0
	v_mov_b32_e32 v2, v194
	v_mov_b32_e32 v3, v182
	v_pk_mul_f32 v[2:3], v[2:3], v[2:3]
	v_mov_b32_e32 v4, v186
	v_mov_b32_e32 v5, v184
	v_add_f32_dpp v0, v0, v0 quad_perm:[1,0,3,2] row_mask:0xf bank_mask:0xf bound_ctrl:1
	v_pk_fma_f32 v[2:3], v[4:5], v[4:5], v[2:3]
	v_mov_b32_e32 v4, v195
	v_mov_b32_e32 v5, v183
	v_add_f32_dpp v0, v0, v0 quad_perm:[2,3,0,1] row_mask:0xf bank_mask:0xf bound_ctrl:1
	v_pk_mul_f32 v[4:5], v[4:5], v[4:5]
	v_mov_b32_e32 v6, v187
	v_mov_b32_e32 v7, v185
	v_add_f32_dpp v0, v0, v0 row_half_mirror row_mask:0xf bank_mask:0xf bound_ctrl:1
	v_pk_fma_f32 v[4:5], v[6:7], v[6:7], v[4:5]
	v_mov_b32_e32 v6, v168
	v_mov_b32_e32 v7, v166
	v_add_f32_dpp v0, v0, v0 row_ror:8 row_mask:0xf bank_mask:0xf bound_ctrl:1
	v_pk_mul_f32 v[6:7], v[6:7], v[6:7]
	v_mov_b32_e32 v8, v169
	v_mov_b32_e32 v9, v167
	v_readlane_b32 s0, v0, 0
	v_readlane_b32 s4, v0, 16
	v_readlane_b32 s1, v0, 32
	v_readlane_b32 s5, v0, 48
	v_pk_fma_f32 v[6:7], v[8:9], v[8:9], v[6:7]
	v_pk_mul_f32 v[8:9], v[120:121], v[120:121]
	v_add_f32_e32 v0, v4, v5
	v_add_f32_e32 v2, v2, v3
	v_pk_fma_f32 v[8:9], v[122:123], v[122:123], v[8:9]
	v_pk_mul_f32 v[158:159], v[92:93], v[92:93]
	v_mov_b32_e32 v160, v136
	v_mov_b32_e32 v161, v134
	v_add_f32_e32 v0, v2, v0
	v_add_f32_e32 v2, v6, v7
	v_pk_fma_f32 v[158:159], v[94:95], v[94:95], v[158:159]
	v_pk_mul_f32 v[160:161], v[160:161], v[160:161]
	v_mov_b32_e32 v164, v137
	v_mov_b32_e32 v165, v135
	v_add_f32_e32 v0, v2, v0
	v_add_f32_e32 v2, v8, v9
	v_pk_fma_f32 v[160:161], v[164:165], v[164:165], v[160:161]
	v_pk_mul_f32 v[164:165], v[64:65], v[64:65]
	v_add_f32_e32 v0, v2, v0
	v_add_f32_e32 v2, v158, v159
	v_pk_fma_f32 v[164:165], v[66:67], v[66:67], v[164:165]
	v_pk_mul_f32 v[174:175], v[50:51], v[50:51]
	v_add_f32_e32 v0, v2, v0
	v_add_f32_e32 v2, v160, v161
	v_pk_fma_f32 v[174:175], v[52:53], v[52:53], v[174:175]
	v_add_f32_e32 v0, v2, v0
	v_add_f32_e32 v2, v164, v165
	v_add_f32_e32 v0, v2, v0
	v_add_f32_e32 v2, v174, v175
	v_add_f32_e32 v0, v2, v0
	v_fmac_f32_e32 v190, 0xba000000, v46
	v_fmac_f32_e32 v192, 0xba000000, v46
	v_mov_b32_e32 v2, v198
	v_mov_b32_e32 v3, v196
	v_pk_mul_f32 v[2:3], v[2:3], v[2:3]
	v_mov_b32_e32 v4, v192
	v_mov_b32_e32 v5, v190
	v_fmac_f32_e32 v197, 0xba000000, v46
	v_fmac_f32_e32 v199, 0xba000000, v46
	v_add_f32_dpp v0, v0, v0 quad_perm:[1,0,3,2] row_mask:0xf bank_mask:0xf bound_ctrl:1
	v_pk_fma_f32 v[2:3], v[4:5], v[4:5], v[2:3]
	v_fmac_f32_e32 v191, 0xba000000, v46
	v_fmac_f32_e32 v193, 0xba000000, v46
	v_mov_b32_e32 v4, v199
	v_mov_b32_e32 v5, v197
	v_add_f32_dpp v0, v0, v0 quad_perm:[2,3,0,1] row_mask:0xf bank_mask:0xf bound_ctrl:1
	v_pk_mul_f32 v[4:5], v[4:5], v[4:5]
	v_mov_b32_e32 v6, v193
	v_mov_b32_e32 v7, v191
	v_fmac_f32_e32 v170, 0xba000000, v46
	v_fmac_f32_e32 v172, 0xba000000, v46
	v_add_f32_dpp v0, v0, v0 row_half_mirror row_mask:0xf bank_mask:0xf bound_ctrl:1
	v_pk_fma_f32 v[4:5], v[6:7], v[6:7], v[4:5]
	v_fmac_f32_e32 v171, 0xba000000, v46
	v_fmac_f32_e32 v173, 0xba000000, v46
	v_mov_b32_e32 v6, v172
	v_mov_b32_e32 v7, v170
	v_add_f32_dpp v0, v0, v0 row_ror:8 row_mask:0xf bank_mask:0xf bound_ctrl:1
	v_pk_mul_f32 v[6:7], v[6:7], v[6:7]
	v_mov_b32_e32 v8, v173
	v_mov_b32_e32 v9, v171
	v_fmac_f32_e32 v145, 0xba000000, v46
	v_fmac_f32_e32 v144, 0xba000000, v46
	v_fmac_f32_e32 v109, 0xba000000, v46
	v_readlane_b32 s18, v0, 0
	v_readlane_b32 s26, v0, 16
	v_readlane_b32 s19, v0, 32
	v_readlane_b32 s27, v0, 48
	v_pk_fma_f32 v[6:7], v[8:9], v[8:9], v[6:7]
	v_fmac_f32_e32 v129, 0xba000000, v46
	v_fmac_f32_e32 v128, 0xba000000, v46
	v_pk_mul_f32 v[8:9], v[144:145], v[144:145]
	v_fmac_f32_e32 v103, 0xba000000, v46
	v_fmac_f32_e32 v107, 0xba000000, v46
	v_mov_b32_e32 v106, v109
	v_fmac_f32_e32 v130, 0xba000000, v46
	v_fmac_f32_e32 v132, 0xba000000, v46
	v_add_f32_e32 v0, v4, v5
	v_add_f32_e32 v2, v2, v3
	v_pk_fma_f32 v[8:9], v[128:129], v[128:129], v[8:9]
	v_fmac_f32_e32 v101, 0xba000000, v46
	v_pk_mul_f32 v[158:159], v[106:107], v[106:107]
	v_mov_b32_e32 v100, v103
	v_fmac_f32_e32 v131, 0xba000000, v46
	v_fmac_f32_e32 v133, 0xba000000, v46
	v_mov_b32_e32 v160, v132
	v_mov_b32_e32 v161, v130
	v_add_f32_e32 v0, v2, v0
	v_add_f32_e32 v2, v6, v7
	v_pk_fma_f32 v[158:159], v[100:101], v[100:101], v[158:159]
	v_pk_mul_f32 v[160:161], v[160:161], v[160:161]
	v_mov_b32_e32 v164, v133
	v_mov_b32_e32 v165, v131
	v_fmac_f32_e32 v75, 0xba000000, v46
	v_fmac_f32_e32 v74, 0xba000000, v46
	v_add_f32_e32 v0, v2, v0
	v_add_f32_e32 v2, v8, v9
	v_pk_fma_f32 v[160:161], v[164:165], v[164:165], v[160:161]
	v_fmac_f32_e32 v69, 0xba000000, v46
	v_fmac_f32_e32 v68, 0xba000000, v46
	v_pk_mul_f32 v[164:165], v[74:75], v[74:75]
	v_fmac_f32_e32 v73, 0xba000000, v46
	v_fmac_f32_e32 v77, 0xba000000, v46
	v_fmac_f32_e32 v76, 0xba000000, v46
	v_add_f32_e32 v0, v2, v0
	v_add_f32_e32 v2, v158, v159
	v_pk_fma_f32 v[164:165], v[68:69], v[68:69], v[164:165]
	v_fmac_f32_e32 v71, 0xba000000, v46
	v_pk_mul_f32 v[174:175], v[76:77], v[76:77]
	v_mov_b32_e32 v70, v73
	v_add_f32_e32 v0, v2, v0
	v_add_f32_e32 v2, v160, v161
	v_pk_fma_f32 v[174:175], v[70:71], v[70:71], v[174:175]
	v_add_f32_e32 v0, v2, v0
	v_add_f32_e32 v2, v164, v165
	v_add_f32_e32 v0, v2, v0
	v_add_f32_e32 v2, v174, v175
	v_add_f32_e32 v0, v2, v0
	global_load_dwordx4 v[2:5], v[16:17], off
	global_load_dwordx4 v[6:9], v[18:19], off
	v_add_f32_dpp v0, v0, v0 quad_perm:[1,0,3,2] row_mask:0xf bank_mask:0xf bound_ctrl:1
	v_pk_mul_f32 v[10:11], v[10:11], v[116:117] op_sel_hi:[1,0]
	v_pk_mul_f32 v[12:13], v[12:13], v[116:117] op_sel_hi:[1,0]
	v_add_f32_dpp v0, v0, v0 quad_perm:[2,3,0,1] row_mask:0xf bank_mask:0xf bound_ctrl:1
	v_lshl_add_u64 v[174:175], s[54:55], 0, v[14:15]
	s_waitcnt vmcnt(0)
	v_pk_fma_f32 v[12:13], v[12:13], v[4:5], v[8:9]
	v_add_f32_dpp v0, v0, v0 row_half_mirror row_mask:0xf bank_mask:0xf bound_ctrl:1
	v_pk_fma_f32 v[10:11], v[10:11], v[2:3], v[6:7]
	global_store_dwordx4 v[174:175], v[10:13], off
	v_add_f32_dpp v0, v0, v0 row_ror:8 row_mask:0xf bank_mask:0xf bound_ctrl:1
	s_nop 0
	v_readlane_b32 s29, v0, 0
	v_readlane_b32 s39, v0, 16
	v_readlane_b32 s38, v0, 32
	v_readlane_b32 s44, v0, 48
	v_cndmask_b32_e64 v0, 0, 1, s[22:23]
	v_cmp_ne_u32_e64 s[2:3], 1, v0
	v_lshlrev_b32_e32 v0, 3, v138
	s_cbranch_vccnz .LBB0_157
	v_bfe_u32 v38, v10, 16, 1
	v_add3_u32 v10, v10, v38, s60
	v_bfe_u32 v38, v11, 16, 1
	v_lshrrev_b32_e32 v10, 16, v10
	v_add3_u32 v11, v11, v38, s60
	v_and_or_b32 v10, v11, s33, v10
	v_bfe_u32 v11, v12, 16, 1
	v_add3_u32 v11, v12, v11, s60
	v_bfe_u32 v12, v13, 16, 1
	v_lshrrev_b32_e32 v11, 16, v11
	v_add3_u32 v12, v13, v12, s60
	v_and_or_b32 v11, v12, s33, v11
	global_store_dwordx2 v0, v[10:11], s[66:67]
